# P6 conv fix-up: hand-written task loop, 14 loads per task issued as one batch
# speedup vs baseline: 1.0031x; 1.0031x over previous
; __device__ __forceinline__ unsigned cvt_pk_bf16(float lo, float hi) { unsigned r; asm volatile("v_cvt_pk_bf16_f32 %0, %1, %2" : "=v"(r) : "v"(lo), "v"(hi)); return r; }
; __device__ __forceinline__ float sigmoid_f(float x) { return fast_rcp(1.0f + fast_exp2(-1.4426950409f * x)); }
; __device__ __forceinline__ f32x4 raw4(const bf16_t* p) { const u32x2 w = *(const u32x2*)p; return (f32x4){bf_lo(w.x), bf_hi(w.x), bf_lo(w.y), bf_hi(w.y)}; }
; __device__ __forceinline__ void conv_fixup(const bf16_t* RAW, const float* ck, const float* cb, bf16_t* ACT, int gtid, int nthr) {
;     constexpr int NJ = FF / 4, NTASK = 128 * 2 * NJ;
;     for (int task = gtid; task < NTASK; task += nthr) {
;         const int j4 = (task % NJ) * 4, rr = task / NJ, grp = rr >> 1, last = rr & 1;
;         const int row = grp * 64 + (last ? 63 : 0);
;         const f32x4 z = {0.f, 0.f, 0.f, 0.f};
;         f32x4 cv[2];
; #pragma unroll
;         for (int bj = 0; bj < 2; ++bj) {
;             const bf16_t* base = RAW + bj * FF + j4;
;             f32x4 pv, cur, nv;
;             if (!last) { pv = grp > 0 ? raw4(base + (size_t)((grp - 1) * 4 + 3) * NUP) : z; cur = raw4(base + (size_t)(grp * 4 + 0) * NUP); nv = raw4(base + (size_t)(grp * 4 + 1) * NUP); }
;             else { pv = raw4(base + (size_t)(grp * 4 + 2) * NUP); cur = raw4(base + (size_t)(grp * 4 + 3) * NUP); nv = grp < 127 ? raw4(base + (size_t)((grp + 1) * 4 + 0) * NUP) : z; }
;             cv[bj] = *(const f32x4*)(ck + 0 * NUP + bj * FF + j4) * pv + *(const f32x4*)(ck + 1 * NUP + bj * FF + j4) * cur + *(const f32x4*)(ck + 2 * NUP + bj * FF + j4) * nv + *(const f32x4*)(cb + bj * FF + j4);
;         }
;         const f32x4 gt = cv[0], vl = cv[1];
;         u32x2 w; w.x = cvt_pk_bf16(gt[0] * sigmoid_f(gt[0]) * vl[0], gt[1] * sigmoid_f(gt[1]) * vl[1]); w.y = cvt_pk_bf16(gt[2] * sigmoid_f(gt[2]) * vl[2], gt[3] * sigmoid_f(gt[3]) * vl[3]);
;         *(u32x2*)(ACT + (size_t)row * FF + j4) = w;
;     }
; }
.Lp6_loop:
	s_mov_b32 s0, 0x2fa0be83
	v_mul_hi_i32 v0, v64, s0
	v_lshrrev_b32_e32 v2, 31, v0
	v_ashrrev_i32_e32 v0, 8, v0
	v_add_u32_e32 v0, v0, v2
	v_mul_i32_i24_e32 v2, 0x560, v0
	v_sub_u32_e32 v2, v64, v2
	v_lshlrev_b32_e32 v36, 2, v2
	v_ashrrev_i32_e32 v66, 1, v0
	v_and_b32_e32 v3, 1, v0
	v_lshlrev_b32_e32 v4, 2, v66
	v_mad_u32_u24 v4, v3, 3, v4
	v_add_u32_e32 v5, -1, v4
	v_max_i32_e32 v5, 0, v5
	v_add_u32_e32 v6, 1, v4
	v_min_i32_e32 v6, 0x1ff, v6
	s_movk_i32 s0, 0x1ff
	v_cmp_ne_u32_e64 s[38:39], 0, v4
	v_cmp_ne_u32_e64 s[40:41], s0, v4
	s_movk_i32 s1, 0x5600
	v_lshlrev_b32_e32 v7, 1, v36
	v_mad_u32_u24 v8, v5, s1, v7
	v_mad_u32_u24 v9, v4, s1, v7
	v_mad_u32_u24 v10, v6, s1, v7
	v_add_u32_e32 v11, 0x2b00, v8
	v_add_u32_e32 v22, 0x2b00, v9
	v_add_u32_e32 v23, 0x2b00, v10
	global_load_dwordx2 v[12:13], v8, s[16:17]
	global_load_dwordx2 v[14:15], v9, s[16:17]
	global_load_dwordx2 v[16:17], v10, s[16:17]
	global_load_dwordx2 v[18:19], v11, s[16:17]
	global_load_dwordx2 v[38:39], v22, s[16:17]
	global_load_dwordx2 v[60:61], v23, s[16:17]
	v_lshlrev_b32_e32 v20, 2, v36
	v_add_u32_e32 v21, 0x5600, v20
	global_load_dwordx4 v[24:27], v20, s[18:19]
	global_load_dwordx4 v[28:31], v20, s[34:35]
	global_load_dwordx4 v[32:35], v20, s[36:37]
	global_load_dwordx4 v[40:43], v20, s[20:21]
	global_load_dwordx4 v[44:47], v21, s[18:19]
	global_load_dwordx4 v[48:51], v21, s[34:35]
	global_load_dwordx4 v[52:55], v21, s[36:37]
	global_load_dwordx4 v[56:59], v21, s[20:21]
	v_lshlrev_b32_e32 v67, 6, v66
	v_mad_u32_u24 v67, v3, 63, v67
	v_mad_u32_u24 v67, v67, s7, v7
	s_waitcnt vmcnt(0)
	v_cndmask_b32_e64 v12, 0, v12, s[38:39]
	v_cndmask_b32_e64 v13, 0, v13, s[38:39]
	v_cndmask_b32_e64 v18, 0, v18, s[38:39]
	v_cndmask_b32_e64 v19, 0, v19, s[38:39]
	v_cndmask_b32_e64 v16, 0, v16, s[40:41]
	v_cndmask_b32_e64 v17, 0, v17, s[40:41]
	v_cndmask_b32_e64 v60, 0, v60, s[40:41]
	v_cndmask_b32_e64 v61, 0, v61, s[40:41]
	v_lshlrev_b32_e32 v68, 16, v12
	v_and_b32_e32 v69, 0xffff0000, v12
	v_lshlrev_b32_e32 v70, 16, v13
	v_and_b32_e32 v71, 0xffff0000, v13
	v_lshlrev_b32_e32 v72, 16, v14
	v_and_b32_e32 v73, 0xffff0000, v14
	v_lshlrev_b32_e32 v74, 16, v15
	v_and_b32_e32 v75, 0xffff0000, v15
	v_lshlrev_b32_e32 v76, 16, v16
	v_and_b32_e32 v77, 0xffff0000, v16
	v_lshlrev_b32_e32 v78, 16, v17
	v_and_b32_e32 v79, 0xffff0000, v17
	v_pk_mul_f32 v[80:81], v[28:29], v[72:73]
	v_pk_fma_f32 v[80:81], v[68:69], v[24:25], v[80:81]
	v_pk_fma_f32 v[80:81], v[76:77], v[32:33], v[80:81]
	v_pk_add_f32 v[80:81], v[40:41], v[80:81]
	v_pk_mul_f32 v[82:83], v[30:31], v[74:75]
	v_pk_fma_f32 v[82:83], v[70:71], v[26:27], v[82:83]
	v_pk_fma_f32 v[82:83], v[78:79], v[34:35], v[82:83]
	v_pk_add_f32 v[82:83], v[42:43], v[82:83]
	v_lshlrev_b32_e32 v68, 16, v18
	v_and_b32_e32 v69, 0xffff0000, v18
	v_lshlrev_b32_e32 v70, 16, v19
	v_and_b32_e32 v71, 0xffff0000, v19
	v_lshlrev_b32_e32 v72, 16, v38
	v_and_b32_e32 v73, 0xffff0000, v38
	v_lshlrev_b32_e32 v74, 16, v39
	v_and_b32_e32 v75, 0xffff0000, v39
	v_lshlrev_b32_e32 v76, 16, v60
	v_and_b32_e32 v77, 0xffff0000, v60
	v_lshlrev_b32_e32 v78, 16, v61
	v_and_b32_e32 v79, 0xffff0000, v61
	v_pk_mul_f32 v[84:85], v[48:49], v[72:73]
	v_pk_fma_f32 v[84:85], v[68:69], v[44:45], v[84:85]
	v_pk_fma_f32 v[84:85], v[76:77], v[52:53], v[84:85]
	v_pk_add_f32 v[84:85], v[56:57], v[84:85]
	v_pk_mul_f32 v[86:87], v[50:51], v[74:75]
	v_pk_fma_f32 v[86:87], v[70:71], v[46:47], v[86:87]
	v_pk_fma_f32 v[86:87], v[78:79], v[54:55], v[86:87]
	v_pk_add_f32 v[86:87], v[58:59], v[86:87]
	v_mul_f32_e32 v88, 0xbfb8aa3b, v80
	v_exp_f32_e32 v88, v88
	v_mul_f32_e32 v89, 0xbfb8aa3b, v81
	v_exp_f32_e32 v89, v89
	v_mul_f32_e32 v90, 0xbfb8aa3b, v82
	v_exp_f32_e32 v90, v90
	v_mul_f32_e32 v91, 0xbfb8aa3b, v83
	v_exp_f32_e32 v91, v91
	s_nop 0
	v_add_f32_e32 v88, 1.0, v88
	v_rcp_f32_e32 v88, v88
	v_add_f32_e32 v89, 1.0, v89
	v_rcp_f32_e32 v89, v89
	v_add_f32_e32 v90, 1.0, v90
	v_rcp_f32_e32 v90, v90
	v_add_f32_e32 v91, 1.0, v91
	v_rcp_f32_e32 v91, v91
	s_nop 0
	v_mul_f32_e32 v88, v80, v88
	v_mul_f32_e32 v88, v88, v84
	v_mul_f32_e32 v89, v81, v89
	v_mul_f32_e32 v89, v89, v85
	v_mul_f32_e32 v90, v82, v90
	v_mul_f32_e32 v90, v90, v86
	v_mul_f32_e32 v91, v83, v91
	v_mul_f32_e32 v91, v91, v87
	v_cvt_pk_bf16_f32 v2, v88, v89
	v_cvt_pk_bf16_f32 v3, v90, v91
	global_store_dwordx2 v67, v[2:3], s[30:31]
	v_add_u32_e32 v64, s80, v64
	s_mov_b32 s0, 0x55fff
	v_cmp_lt_i32_e32 vcc, s0, v64
	s_nop 1
	s_or_b64 s[42:43], vcc, s[42:43]
	s_andn2_b64 exec, exec, s[42:43]
	s_cbranch_execnz .Lp6_loop
